# norm1/norm2 row loops: the 24 gain/scale/shift table loads of a row issued together in own registers instead of 8 serial load-wait-compute-store chunks
# speedup vs baseline: 1.0178x; 1.0095x over previous
; #define GAS __attribute__((address_space(1)))
; DI void phase_norm(const Ctx& C, const float* xlat, const float* xctx, bf16_t* H, const float* gn, const float* modl, int sh_off, int sc_off, int nrows, const float* part, int nsplit, float* xs_out) {
;     ...
;         const int b = row < NLAT ? (row >> 11) : 4;
;         const float* mb = modl + (size_t)b * MODW;
;         const GAS f32x4* xr = (const GAS f32x4*)(row < NLAT ? xlat + (size_t)row * DM : xctx + (size_t)(row - NLAT) * DM) + lane;
;         f32x4 v[8]; float s = 0.f;
; #pragma unroll
;         for (int j = 0; j < 8; ++j) v[j] = __builtin_nontemporal_load(xr + 64 * j);
;         if (part != nullptr && row >= NLAT) {
;             for (int kb = 0; kb < nsplit; kb += 4) {
;                 f32x4 t[4][8];
; #pragma unroll
;                 for (int q = 0; q < 4; ++q) { const GAS f32x4* pr = (const GAS f32x4*)(part + ((size_t)(kb + q) * NCTX + (row - NLAT)) * DM) + lane;
; #pragma unroll
;                     for (int j = 0; j < 8; ++j) t[q][j] = __builtin_nontemporal_load(pr + 64 * j); }
; #pragma unroll
;                 for (int j = 0; j < 8; ++j) v[j] += (t[0][j] + t[1][j]) + (t[2][j] + t[3][j]); }
;             GAS f32x4* xo = (GAS f32x4*)(xs_out + (size_t)row * DM) + lane;
; #pragma unroll
;             for (int j = 0; j < 8; ++j) xo[64 * j] = v[j];
;         }
; #pragma unroll
;         for (int j = 0; j < 8; ++j) s += (v[j].x * v[j].x + v[j].y * v[j].y) + (v[j].z * v[j].z + v[j].w * v[j].w);
.LBB0_155:
	v_lshl_add_u64 v[2:3], v[206:207], 4, s[12:13]
	global_load_dwordx4 v[30:33], v[2:3], off nt
	global_load_dwordx4 v[26:29], v[2:3], off offset:1024 nt
	global_load_dwordx4 v[22:25], v[2:3], off offset:2048 nt
	global_load_dwordx4 v[18:21], v[2:3], off offset:3072 nt
	v_add_co_u32_e32 v2, vcc, s41, v2
	s_ashr_i32 s0, s4, 11
	s_nop 0
	v_addc_co_u32_e32 v3, vcc, 0, v3, vcc
	global_load_dwordx4 v[14:17], v[2:3], off nt
	global_load_dwordx4 v[10:13], v[2:3], off offset:1024 nt
	global_load_dwordx4 v[6:9], v[2:3], off offset:2048 nt
	s_nop 0
	global_load_dwordx4 v[2:5], v[2:3], off offset:3072 nt
	s_mul_hi_i32 s1, s0, 0xc000
	s_mul_i32 s0, s0, 0xc000
	s_add_u32 s20, s92, s0
	s_addc_u32 s21, s56, s1
	v_lshl_add_u64 v[54:55], v[38:39], 2, s[20:21]
	v_add_co_u32_e32 v82, vcc, s47, v54
	v_lshl_add_u64 v[194:195], v[54:55], 0, s[22:23]
	s_nop 0
	v_addc_co_u32_e32 v83, vcc, 0, v55, vcc
	v_add_co_u32_e32 v134, vcc, s85, v54
	v_lshl_add_u64 v[154:155], v[54:55], 0, s[24:25]
	s_nop 0
	v_addc_co_u32_e32 v135, vcc, 0, v55, vcc
	global_load_dwordx4 v[158:161], v[40:41], off
	global_load_dwordx4 v[162:165], v[82:83], off offset:-4096
	global_load_dwordx4 v[166:169], v[134:135], off offset:-4096
	global_load_dwordx4 v[170:173], v[40:41], off offset:1024
	global_load_dwordx4 v[174:177], v[194:195], off offset:1024
	global_load_dwordx4 v[178:181], v[154:155], off offset:1024
	global_load_dwordx4 v[182:185], v[40:41], off offset:2048
	global_load_dwordx4 v[186:189], v[194:195], off offset:2048
	global_load_dwordx4 v[190:193], v[154:155], off offset:2048
	global_load_dwordx4 v[210:213], v[40:41], off offset:3072
	global_load_dwordx4 v[214:217], v[194:195], off offset:3072
	global_load_dwordx4 v[218:221], v[154:155], off offset:3072
	global_load_dwordx4 v[222:225], v[42:43], off
	global_load_dwordx4 v[240:243], v[82:83], off
	global_load_dwordx4 v[244:247], v[134:135], off
	global_load_dwordx4 v[138:141], v[44:45], off
	global_load_dwordx4 v[142:145], v[82:83], off offset:1024
	global_load_dwordx4 v[146:149], v[134:135], off offset:1024
	global_load_dwordx4 v[150:153], v[46:47], off
	global_load_dwordx4 v[74:77], v[82:83], off offset:2048
	global_load_dwordx4 v[78:81], v[134:135], off offset:2048
	global_load_dwordx4 v[202:205], v[48:49], off
	global_load_dwordx4 v[56:59], v[82:83], off offset:3072
	global_load_dwordx4 v[130:133], v[134:135], off offset:3072
	s_add_i32 s4, s4, s10
	s_add_u32 s12, s12, s14
	s_addc_u32 s13, s13, s15
	s_waitcnt vmcnt(23)
	v_mov_b32_e32 v36, v31
	v_mov_b32_e32 v37, v27
	v_mov_b32_e32 v34, v30
	v_mov_b32_e32 v35, v26
	v_pk_mul_f32 v[36:37], v[36:37], v[36:37]
	v_mov_b32_e32 v50, v33
	v_mov_b32_e32 v51, v29
	v_pk_fma_f32 v[34:35], v[34:35], v[34:35], v[36:37]
	v_mov_b32_e32 v36, v32
	v_mov_b32_e32 v37, v28
	v_pk_mul_f32 v[50:51], v[50:51], v[50:51]
	v_mul_f32_e32 v0, v14, v14
	v_pk_fma_f32 v[36:37], v[36:37], v[36:37], v[50:51]
	v_pk_mul_f32 v[50:51], v[22:23], v[22:23]
	v_pk_add_f32 v[34:35], v[34:35], v[36:37]
	v_pk_mul_f32 v[36:37], v[24:25], v[24:25]
	v_pk_add_f32 v[34:35], v[34:35], v[34:35] op_sel:[0,1] op_sel_hi:[1,0]
	v_pk_mov_b32 v[52:53], v[50:51], v[36:37] op_sel:[1,0]
	v_mov_b32_e32 v51, v37
	v_pk_add_f32 v[36:37], v[52:53], v[50:51]
	v_mul_f32_e32 v50, v15, v15
	v_pk_add_f32 v[36:37], v[36:37], v[36:37] op_sel:[0,1] op_sel_hi:[1,0]
	v_mov_b32_e32 v35, v0
	v_mov_b32_e32 v37, v50
	v_mul_f32_e32 v0, v19, v19
	v_mul_f32_e32 v51, v16, v16
	v_pk_add_f32 v[34:35], v[34:35], v[36:37]
	v_pk_fma_f32 v[36:37], v[18:19], v[18:19], v[0:1] op_sel_hi:[1,1,0]
	v_mul_f32_e32 v0, v21, v21
	v_mul_f32_e32 v52, v17, v17
	v_mov_b32_e32 v37, v51
	v_pk_fma_f32 v[50:51], v[20:21], v[20:21], v[0:1] op_sel_hi:[1,1,0]
	v_mul_f32_e32 v0, v2, v2
	v_mov_b32_e32 v51, v52
	v_pk_add_f32 v[36:37], v[36:37], v[50:51]
	v_pk_mul_f32 v[50:51], v[10:11], v[10:11]
	v_pk_add_f32 v[34:35], v[34:35], v[36:37]
	v_pk_mul_f32 v[36:37], v[12:13], v[12:13]
	v_pk_add_f32 v[34:35], v[34:35], v[34:35] op_sel:[0,1] op_sel_hi:[1,0]
	v_pk_mov_b32 v[52:53], v[50:51], v[36:37] op_sel:[1,0]
	v_mov_b32_e32 v51, v37
	v_pk_add_f32 v[36:37], v[52:53], v[50:51]
	v_mul_f32_e32 v50, v3, v3
	v_pk_add_f32 v[36:37], v[36:37], v[36:37] op_sel:[0,1] op_sel_hi:[1,0]
	v_mov_b32_e32 v35, v0
	v_mov_b32_e32 v37, v50
	v_mul_f32_e32 v0, v7, v7
	v_mul_f32_e32 v51, v4, v4
	v_pk_add_f32 v[34:35], v[34:35], v[36:37]
	v_pk_fma_f32 v[36:37], v[6:7], v[6:7], v[0:1] op_sel_hi:[1,1,0]
	v_mul_f32_e32 v0, v9, v9
	v_mul_f32_e32 v52, v5, v5
	v_mov_b32_e32 v37, v51
	v_pk_fma_f32 v[50:51], v[8:9], v[8:9], v[0:1] op_sel_hi:[1,1,0]
	s_nop 0
	v_mov_b32_e32 v51, v52
	v_pk_add_f32 v[36:37], v[36:37], v[50:51]
	s_nop 0
	v_pk_add_f32 v[34:35], v[34:35], v[36:37]
	s_nop 0
	v_add_f32_e32 v0, v34, v35
	ds_bpermute_b32 v34, v60, v0
	s_waitcnt lgkmcnt(0)
	v_add_f32_e32 v0, v0, v34
	ds_bpermute_b32 v34, v61, v0
	s_waitcnt lgkmcnt(0)
	v_add_f32_e32 v0, v0, v34
	ds_bpermute_b32 v34, v62, v0
	s_waitcnt lgkmcnt(0)
	v_add_f32_e32 v0, v0, v34
	ds_bpermute_b32 v34, v63, v0
	s_waitcnt lgkmcnt(0)
	v_add_f32_e32 v0, v0, v34
	ds_bpermute_b32 v34, v64, v0
	s_waitcnt lgkmcnt(0)
	v_add_f32_e32 v0, v0, v34
	ds_bpermute_b32 v34, v65, v0
	s_waitcnt lgkmcnt(0)
; #define GAS __attribute__((address_space(1)))
; DI unsigned pk2(float lo, float hi) { f32x2 v = {lo, hi}; bf16x2_t b = __builtin_convertvector(v, bf16x2_t); return __builtin_bit_cast(unsigned, b); }
; DI void phase_norm(const Ctx& C, const float* xlat, const float* xctx, bf16_t* H, const float* gn, const float* modl, int sh_off, int sc_off, int nrows, const float* part, int nsplit, float* xs_out) {
;     ...
;         const float rstd = 1.f / sqrtf(wave_sum(s, lane) * (1.f / DM) + EPS);
;         GAS u32x2* o8 = (GAS u32x2*)(H + (size_t)row * DM) + lane;
; #pragma unroll
;         for (int j = 0; j < 8; ++j) { const int col = 4 * lane + 256 * j;
;             const f32x4 g = *(const GAS f32x4*)(gn + col), sc = *(const GAS f32x4*)(mb + sc_off + col), sh = *(const GAS f32x4*)(mb + sh_off + col);
;             const f32x4 y = v[j] * rstd * g * (sc + 1.f) + sh;
;             u32x2 w; w.x = pk2(y.x, y.y); w.y = pk2(y.z, y.w); o8[64 * j] = w; }
	v_add_f32_e32 v0, v0, v34
	v_fmamk_f32 v0, v0, 0x3a000000, v227
	v_cmp_gt_f32_e32 vcc, s67, v0
	v_mul_f32_e32 v34, 0x4f800000, v0
	s_nop 0
	v_cndmask_b32_e32 v0, v0, v34, vcc
	v_sqrt_f32_e32 v34, v0
	s_nop 0
	v_add_u32_e32 v35, -1, v34
	v_fma_f32 v36, -v35, v34, v0
	v_cmp_ge_f32_e64 s[0:1], 0, v36
	v_add_u32_e32 v36, 1, v34
	s_nop 0
	v_cndmask_b32_e64 v35, v34, v35, s[0:1]
	v_fma_f32 v34, -v36, v34, v0
	v_cmp_lt_f32_e64 s[0:1], 0, v34
	s_nop 1
	v_cndmask_b32_e64 v34, v35, v36, s[0:1]
	v_mul_f32_e32 v35, 0x37800000, v34
	v_cndmask_b32_e32 v34, v34, v35, vcc
	v_cmp_class_f32_e32 vcc, v0, v228
	s_nop 1
	v_cndmask_b32_e32 v0, v34, v0, vcc
	v_div_scale_f32 v34, s[0:1], v0, v0, 1.0
	v_rcp_f32_e32 v35, v34
	s_nop 0
	v_fma_f32 v36, -v34, v35, 1.0
	v_fmac_f32_e32 v35, v36, v35
	v_div_scale_f32 v36, vcc, 1.0, v0, 1.0
	v_mul_f32_e32 v37, v36, v35
	v_fma_f32 v50, -v34, v37, v36
	v_fmac_f32_e32 v37, v50, v35
	v_fma_f32 v34, -v34, v37, v36
	v_div_fmas_f32 v34, v34, v35, v37
	v_div_fixup_f32 v0, v34, v0, 1.0
	s_nop 0
	s_nop 0
	v_pk_mul_f32 v[32:33], v[32:33], v[0:1] op_sel_hi:[1,0]
	v_pk_mul_f32 v[30:31], v[30:31], v[0:1] op_sel_hi:[1,0]
	v_pk_mul_f32 v[32:33], v[160:161], v[32:33]
	v_pk_mul_f32 v[30:31], v[158:159], v[30:31]
	v_lshl_add_u64 v[50:51], v[206:207], 3, s[16:17]
	v_pk_mul_f32 v[28:29], v[28:29], v[0:1] op_sel_hi:[1,0]
	v_pk_mul_f32 v[26:27], v[26:27], v[0:1] op_sel_hi:[1,0]
	v_pk_mul_f32 v[24:25], v[24:25], v[0:1] op_sel_hi:[1,0]
	v_pk_mul_f32 v[22:23], v[22:23], v[0:1] op_sel_hi:[1,0]
	v_pk_mul_f32 v[20:21], v[20:21], v[0:1] op_sel_hi:[1,0]
	v_pk_mul_f32 v[18:19], v[18:19], v[0:1] op_sel_hi:[1,0]
	v_pk_mul_f32 v[16:17], v[16:17], v[0:1] op_sel_hi:[1,0]
	v_pk_mul_f32 v[14:15], v[14:15], v[0:1] op_sel_hi:[1,0]
	v_pk_mul_f32 v[12:13], v[12:13], v[0:1] op_sel_hi:[1,0]
	v_pk_mul_f32 v[10:11], v[10:11], v[0:1] op_sel_hi:[1,0]
	v_pk_mul_f32 v[8:9], v[8:9], v[0:1] op_sel_hi:[1,0]
	v_pk_mul_f32 v[6:7], v[6:7], v[0:1] op_sel_hi:[1,0]
	v_pk_mul_f32 v[4:5], v[4:5], v[0:1] op_sel_hi:[1,0]
	v_pk_mul_f32 v[2:3], v[2:3], v[0:1] op_sel_hi:[1,0]
	s_add_u32 s16, s16, s18
	s_addc_u32 s17, s17, s19
	s_cmpk_gt_i32 s4, 0x1fff
	s_waitcnt vmcnt(0)
	v_pk_add_f32 v[66:67], v[164:165], 1.0 op_sel_hi:[1,0]
	v_pk_add_f32 v[68:69], v[162:163], 1.0 op_sel_hi:[1,0]
	v_pk_fma_f32 v[32:33], v[66:67], v[32:33], v[168:169]
	v_pk_fma_f32 v[30:31], v[68:69], v[30:31], v[166:167]
	s_nop 0
	v_cvt_pk_bf16_f32 v30, v30, v31
	v_cvt_pk_bf16_f32 v31, v32, v33
	global_store_dwordx2 v[50:51], v[30:31], off
	s_nop 0
	v_pk_mul_f32 v[26:27], v[170:171], v[26:27]
	v_pk_mul_f32 v[28:29], v[172:173], v[28:29]
	v_pk_add_f32 v[30:31], v[176:177], 1.0 op_sel_hi:[1,0]
	v_pk_add_f32 v[32:33], v[174:175], 1.0 op_sel_hi:[1,0]
	v_pk_fma_f32 v[28:29], v[30:31], v[28:29], v[180:181]
	v_pk_fma_f32 v[26:27], v[32:33], v[26:27], v[178:179]
	s_nop 0
	v_cvt_pk_bf16_f32 v26, v26, v27
	v_cvt_pk_bf16_f32 v27, v28, v29
	global_store_dwordx2 v[50:51], v[26:27], off offset:512
	s_nop 0
	v_pk_mul_f32 v[22:23], v[182:183], v[22:23]
	v_pk_mul_f32 v[24:25], v[184:185], v[24:25]
	v_pk_add_f32 v[26:27], v[188:189], 1.0 op_sel_hi:[1,0]
	v_pk_add_f32 v[28:29], v[186:187], 1.0 op_sel_hi:[1,0]
	v_pk_fma_f32 v[24:25], v[26:27], v[24:25], v[192:193]
	v_pk_fma_f32 v[22:23], v[28:29], v[22:23], v[190:191]
	s_nop 0
	v_cvt_pk_bf16_f32 v22, v22, v23
	v_cvt_pk_bf16_f32 v23, v24, v25
	global_store_dwordx2 v[50:51], v[22:23], off offset:1024
	s_nop 0
	v_pk_mul_f32 v[18:19], v[18:19], v[210:211]
	v_pk_mul_f32 v[20:21], v[20:21], v[212:213]
	v_pk_add_f32 v[22:23], v[216:217], 1.0 op_sel_hi:[1,0]
	v_pk_add_f32 v[24:25], v[214:215], 1.0 op_sel_hi:[1,0]
	v_pk_fma_f32 v[20:21], v[20:21], v[22:23], v[220:221]
	v_pk_fma_f32 v[18:19], v[18:19], v[24:25], v[218:219]
	s_nop 0
	v_cvt_pk_bf16_f32 v18, v18, v19
	v_cvt_pk_bf16_f32 v19, v20, v21
	global_store_dwordx2 v[50:51], v[18:19], off offset:1536
	s_nop 0
	v_pk_mul_f32 v[14:15], v[14:15], v[222:223]
	v_pk_mul_f32 v[16:17], v[16:17], v[224:225]
	v_pk_add_f32 v[18:19], v[242:243], 1.0 op_sel_hi:[1,0]
	v_pk_add_f32 v[20:21], v[240:241], 1.0 op_sel_hi:[1,0]
	v_pk_fma_f32 v[16:17], v[16:17], v[18:19], v[246:247]
	v_pk_fma_f32 v[14:15], v[14:15], v[20:21], v[244:245]
	s_nop 0
	v_cvt_pk_bf16_f32 v14, v14, v15
	v_cvt_pk_bf16_f32 v15, v16, v17
	global_store_dwordx2 v[50:51], v[14:15], off offset:2048
	s_nop 0
	v_pk_mul_f32 v[10:11], v[10:11], v[138:139]
	v_pk_mul_f32 v[12:13], v[12:13], v[140:141]
	v_pk_add_f32 v[14:15], v[144:145], 1.0 op_sel_hi:[1,0]
	v_pk_add_f32 v[16:17], v[142:143], 1.0 op_sel_hi:[1,0]
	v_pk_fma_f32 v[12:13], v[12:13], v[14:15], v[148:149]
	v_pk_fma_f32 v[10:11], v[10:11], v[16:17], v[146:147]
	s_nop 0
	v_cvt_pk_bf16_f32 v10, v10, v11
	v_cvt_pk_bf16_f32 v11, v12, v13
	global_store_dwordx2 v[50:51], v[10:11], off offset:2560
	s_nop 0
	v_pk_mul_f32 v[6:7], v[6:7], v[150:151]
	v_pk_mul_f32 v[8:9], v[8:9], v[152:153]
	v_pk_add_f32 v[10:11], v[76:77], 1.0 op_sel_hi:[1,0]
	v_pk_add_f32 v[12:13], v[74:75], 1.0 op_sel_hi:[1,0]
	v_pk_fma_f32 v[8:9], v[8:9], v[10:11], v[80:81]
	v_pk_fma_f32 v[6:7], v[6:7], v[12:13], v[78:79]
	s_nop 0
	v_cvt_pk_bf16_f32 v6, v6, v7
	v_cvt_pk_bf16_f32 v7, v8, v9
	global_store_dwordx2 v[50:51], v[6:7], off offset:3072
	s_nop 0
	v_pk_mul_f32 v[2:3], v[2:3], v[202:203]
	v_pk_mul_f32 v[4:5], v[4:5], v[204:205]
	v_pk_add_f32 v[6:7], v[58:59], 1.0 op_sel_hi:[1,0]
	v_pk_add_f32 v[8:9], v[56:57], 1.0 op_sel_hi:[1,0]
	v_pk_fma_f32 v[4:5], v[4:5], v[6:7], v[132:133]
	v_pk_fma_f32 v[2:3], v[2:3], v[8:9], v[130:131]
	s_nop 0
	v_cvt_pk_bf16_f32 v2, v2, v3
	v_cvt_pk_bf16_f32 v3, v4, v5
	global_store_dwordx2 v[50:51], v[2:3], off offset:3584
	s_cbranch_scc0 .LBB0_155

; #define GAS __attribute__((address_space(1)))
; DI void phase_norm(const Ctx& C, const float* xlat, const float* xctx, bf16_t* H, const float* gn, const float* modl, int sh_off, int sc_off, int nrows, const float* part, int nsplit, float* xs_out) {
;     ...
;         for (int j = 0; j < 8; ++j) s += (v[j].x * v[j].x + v[j].y * v[j].y) + (v[j].z * v[j].z + v[j].w * v[j].w);
;         const float rstd = 1.f / sqrtf(wave_sum(s, lane) * (1.f / DM) + EPS);
;         GAS u32x2* o8 = (GAS u32x2*)(H + (size_t)row * DM) + lane;
; #pragma unroll
;         for (int j = 0; j < 8; ++j) { const int col = 4 * lane + 256 * j;
;             const f32x4 g = *(const GAS f32x4*)(gn + col), sc = *(const GAS f32x4*)(mb + sc_off + col), sh = *(const GAS f32x4*)(mb + sh_off + col);
.LBB0_160:
	s_waitcnt vmcnt(0)
	v_mov_b32_e32 v36, v31
	v_mov_b32_e32 v37, v27
	v_mov_b32_e32 v34, v30
	v_mov_b32_e32 v35, v26
	v_pk_mul_f32 v[36:37], v[36:37], v[36:37]
	v_mov_b32_e32 v38, v33
	v_mov_b32_e32 v39, v29
	v_pk_fma_f32 v[34:35], v[34:35], v[34:35], v[36:37]
	v_mov_b32_e32 v36, v32
	v_mov_b32_e32 v37, v28
	v_pk_mul_f32 v[38:39], v[38:39], v[38:39]
	s_min_i32 s0, s4, 0x2000
	v_pk_fma_f32 v[36:37], v[36:37], v[36:37], v[38:39]
	v_pk_mul_f32 v[38:39], v[22:23], v[22:23]
	v_pk_add_f32 v[34:35], v[34:35], v[36:37]
	v_pk_mul_f32 v[36:37], v[24:25], v[24:25]
	v_pk_add_f32 v[34:35], v[34:35], v[34:35] op_sel:[0,1] op_sel_hi:[1,0]
	v_pk_mov_b32 v[40:41], v[38:39], v[36:37] op_sel:[1,0]
	v_mov_b32_e32 v39, v37
	v_pk_add_f32 v[36:37], v[40:41], v[38:39]
	v_mul_f32_e32 v38, v14, v14
	v_mul_f32_e32 v39, v15, v15
	v_pk_add_f32 v[36:37], v[36:37], v[36:37] op_sel:[0,1] op_sel_hi:[1,0]
	v_mov_b32_e32 v35, v38
	v_mov_b32_e32 v37, v39
	v_pk_add_f32 v[34:35], v[34:35], v[36:37]
	v_mul_f32_e32 v36, v19, v19
	v_mul_f32_e32 v38, v21, v21
	v_mul_f32_e32 v40, v16, v16
	v_mul_f32_e32 v41, v17, v17
	v_pk_fma_f32 v[36:37], v[18:19], v[18:19], v[36:37] op_sel_hi:[1,1,0]
	v_pk_fma_f32 v[38:39], v[20:21], v[20:21], v[38:39] op_sel_hi:[1,1,0]
	v_mov_b32_e32 v37, v40
	v_mov_b32_e32 v39, v41
	v_pk_add_f32 v[36:37], v[36:37], v[38:39]
	v_pk_mul_f32 v[38:39], v[10:11], v[10:11]
	v_pk_add_f32 v[34:35], v[34:35], v[36:37]
	v_pk_mul_f32 v[36:37], v[12:13], v[12:13]
	s_ashr_i32 s0, s0, 11
	v_pk_mov_b32 v[40:41], v[38:39], v[36:37] op_sel:[1,0]
	v_mov_b32_e32 v39, v37
	v_pk_add_f32 v[36:37], v[40:41], v[38:39]
	s_mul_hi_i32 s1, s0, 0xc000
	s_mul_i32 s0, s0, 0xc000
	v_mul_f32_e32 v38, v2, v2
	v_mul_f32_e32 v39, v3, v3
	v_pk_add_f32 v[34:35], v[34:35], v[34:35] op_sel:[0,1] op_sel_hi:[1,0]
	v_pk_add_f32 v[36:37], v[36:37], v[36:37] op_sel:[0,1] op_sel_hi:[1,0]
	s_add_u32 s0, s92, s0
	v_mov_b32_e32 v35, v38
	v_mov_b32_e32 v37, v39
	s_addc_u32 s1, s56, s1
	v_pk_add_f32 v[34:35], v[34:35], v[36:37]
	v_mul_f32_e32 v36, v7, v7
	v_mul_f32_e32 v38, v9, v9
	v_mul_f32_e32 v40, v4, v4
	v_mul_f32_e32 v41, v5, v5
	v_pk_fma_f32 v[36:37], v[6:7], v[6:7], v[36:37] op_sel_hi:[1,1,0]
	v_pk_fma_f32 v[38:39], v[8:9], v[8:9], v[38:39] op_sel_hi:[1,1,0]
	v_lshl_add_u64 v[46:47], v[122:123], 2, s[0:1]
	v_mov_b32_e32 v37, v40
	v_mov_b32_e32 v39, v41
	v_add_co_u32_e32 v48, vcc, s47, v46
	v_pk_add_f32 v[36:37], v[36:37], v[38:39]
	s_nop 0
	v_addc_co_u32_e32 v49, vcc, 0, v47, vcc
	v_pk_add_f32 v[34:35], v[34:35], v[36:37]
	v_add_co_u32_e32 v50, vcc, s85, v46
	v_add_f32_e32 v52, v34, v35
	global_load_dwordx4 v[34:37], v[124:125], off
	global_load_dwordx4 v[38:41], v[48:49], off offset:-4096
	v_addc_co_u32_e32 v51, vcc, 0, v47, vcc
	v_lshl_add_u64 v[134:135], v[46:47], 0, s[60:61]
	v_lshl_add_u64 v[154:155], v[46:47], 0, s[80:81]
	global_load_dwordx4 v[68:71], v[124:125], off offset:1024
	global_load_dwordx4 v[72:75], v[134:135], off offset:1024
	global_load_dwordx4 v[76:79], v[154:155], off offset:1024
	global_load_dwordx4 v[80:83], v[124:125], off offset:2048
	global_load_dwordx4 v[138:141], v[134:135], off offset:2048
	global_load_dwordx4 v[142:145], v[154:155], off offset:2048
	global_load_dwordx4 v[146:149], v[124:125], off offset:3072
	global_load_dwordx4 v[150:153], v[134:135], off offset:3072
	global_load_dwordx4 v[158:161], v[154:155], off offset:3072
	global_load_dwordx4 v[162:165], v[126:127], off
	global_load_dwordx4 v[174:177], v[48:49], off
	global_load_dwordx4 v[178:181], v[50:51], off
	global_load_dwordx4 v[182:185], v[128:129], off
	global_load_dwordx4 v[186:189], v[48:49], off offset:1024
	global_load_dwordx4 v[190:193], v[50:51], off offset:1024
	global_load_dwordx4 v[202:205], v[130:131], off
	global_load_dwordx4 v[210:213], v[48:49], off offset:2048
	global_load_dwordx4 v[214:217], v[50:51], off offset:2048
	global_load_dwordx4 v[218:221], v[132:133], off
	global_load_dwordx4 v[222:225], v[48:49], off offset:3072
	global_load_dwordx4 v[240:243], v[50:51], off offset:3072
	global_load_dwordx4 v[42:45], v[50:51], off offset:-4096
	ds_bpermute_b32 v53, v0, v52
	s_add_u32 s4, s4, s10
	s_addc_u32 s5, s5, s11
	s_waitcnt lgkmcnt(0)
	v_add_f32_e32 v52, v52, v53
	ds_bpermute_b32 v53, v168, v52
	s_waitcnt lgkmcnt(0)
	v_add_f32_e32 v52, v52, v53
	ds_bpermute_b32 v53, v169, v52
	s_waitcnt lgkmcnt(0)
	v_add_f32_e32 v52, v52, v53
	ds_bpermute_b32 v53, v170, v52
	s_waitcnt lgkmcnt(0)
	v_add_f32_e32 v52, v52, v53
	ds_bpermute_b32 v53, v171, v52
	s_waitcnt lgkmcnt(0)
	v_add_f32_e32 v52, v52, v53
	ds_bpermute_b32 v53, v172, v52
	s_waitcnt lgkmcnt(0)
; #define GAS __attribute__((address_space(1)))
; DI unsigned pk2(float lo, float hi) { f32x2 v = {lo, hi}; bf16x2_t b = __builtin_convertvector(v, bf16x2_t); return __builtin_bit_cast(unsigned, b); }
; DI void phase_norm(const Ctx& C, const float* xlat, const float* xctx, bf16_t* H, const float* gn, const float* modl, int sh_off, int sc_off, int nrows, const float* part, int nsplit, float* xs_out) {
;     ...
;         const float rstd = 1.f / sqrtf(wave_sum(s, lane) * (1.f / DM) + EPS);
;         GAS u32x2* o8 = (GAS u32x2*)(H + (size_t)row * DM) + lane;
; #pragma unroll
;         for (int j = 0; j < 8; ++j) { const int col = 4 * lane + 256 * j;
;             const f32x4 g = *(const GAS f32x4*)(gn + col), sc = *(const GAS f32x4*)(mb + sc_off + col), sh = *(const GAS f32x4*)(mb + sh_off + col);
;             const f32x4 y = v[j] * rstd * g * (sc + 1.f) + sh;
;             u32x2 w; w.x = pk2(y.x, y.y); w.y = pk2(y.z, y.w); o8[64 * j] = w; }
	v_add_f32_e32 v52, v52, v53
	v_fmamk_f32 v52, v52, 0x3a000000, v227
	v_mul_f32_e32 v53, 0x4f800000, v52
	v_cmp_gt_f32_e32 vcc, s67, v52
	s_nop 1
	v_cndmask_b32_e32 v52, v52, v53, vcc
	v_sqrt_f32_e32 v53, v52
	s_nop 0
	v_add_u32_e32 v54, -1, v53
	v_fma_f32 v55, -v54, v53, v52
	v_cmp_ge_f32_e64 s[0:1], 0, v55
	v_add_u32_e32 v55, 1, v53
	s_nop 0
	v_cndmask_b32_e64 v54, v53, v54, s[0:1]
	v_fma_f32 v53, -v55, v53, v52
	v_cmp_lt_f32_e64 s[0:1], 0, v53
	s_nop 1
	v_cndmask_b32_e64 v53, v54, v55, s[0:1]
	v_mul_f32_e32 v54, 0x37800000, v53
	v_cndmask_b32_e32 v53, v53, v54, vcc
	v_cmp_class_f32_e32 vcc, v52, v228
	s_nop 1
	v_cndmask_b32_e32 v52, v53, v52, vcc
	v_div_scale_f32 v53, s[0:1], v52, v52, 1.0
	v_rcp_f32_e32 v54, v53
	s_nop 0
	v_fma_f32 v55, -v53, v54, 1.0
	v_fmac_f32_e32 v54, v55, v54
	v_div_scale_f32 v55, vcc, 1.0, v52, 1.0
	v_mul_f32_e32 v56, v55, v54
	v_fma_f32 v57, -v53, v56, v55
	v_fmac_f32_e32 v56, v57, v54
	v_fma_f32 v53, -v53, v56, v55
	v_div_fmas_f32 v53, v53, v54, v56
	v_div_fixup_f32 v52, v53, v52, 1.0
	v_pk_mul_f32 v[32:33], v[32:33], v[52:53] op_sel_hi:[1,0]
	v_pk_mul_f32 v[30:31], v[30:31], v[52:53] op_sel_hi:[1,0]
	s_waitcnt vmcnt(0)
	v_pk_mul_f32 v[32:33], v[36:37], v[32:33]
	v_pk_mul_f32 v[30:31], v[34:35], v[30:31]
	v_pk_add_f32 v[34:35], v[40:41], 1.0 op_sel_hi:[1,0]
	v_pk_add_f32 v[36:37], v[38:39], 1.0 op_sel_hi:[1,0]
	v_pk_fma_f32 v[32:33], v[34:35], v[32:33], v[44:45]
	v_pk_fma_f32 v[30:31], v[36:37], v[30:31], v[42:43]
	v_lshl_add_u64 v[54:55], v[206:207], 3, s[12:13]
	v_cvt_pk_bf16_f32 v30, v30, v31
	v_cvt_pk_bf16_f32 v31, v32, v33
	global_store_dwordx2 v[54:55], v[30:31], off
	v_pk_mul_f32 v[28:29], v[28:29], v[52:53] op_sel_hi:[1,0]
	v_pk_mul_f32 v[26:27], v[26:27], v[52:53] op_sel_hi:[1,0]
	v_pk_mul_f32 v[24:25], v[24:25], v[52:53] op_sel_hi:[1,0]
	v_pk_mul_f32 v[22:23], v[22:23], v[52:53] op_sel_hi:[1,0]
	v_pk_mul_f32 v[20:21], v[20:21], v[52:53] op_sel_hi:[1,0]
	v_pk_mul_f32 v[18:19], v[18:19], v[52:53] op_sel_hi:[1,0]
	v_pk_mul_f32 v[16:17], v[16:17], v[52:53] op_sel_hi:[1,0]
	v_pk_mul_f32 v[14:15], v[14:15], v[52:53] op_sel_hi:[1,0]
	v_pk_mul_f32 v[12:13], v[12:13], v[52:53] op_sel_hi:[1,0]
	v_pk_mul_f32 v[10:11], v[10:11], v[52:53] op_sel_hi:[1,0]
	v_pk_mul_f32 v[8:9], v[8:9], v[52:53] op_sel_hi:[1,0]
	v_pk_mul_f32 v[6:7], v[6:7], v[52:53] op_sel_hi:[1,0]
	v_pk_mul_f32 v[4:5], v[4:5], v[52:53] op_sel_hi:[1,0]
	v_pk_mul_f32 v[2:3], v[2:3], v[52:53] op_sel_hi:[1,0]
	s_add_u32 s12, s12, s14
	s_addc_u32 s13, s13, s15
	s_cmp_ge_i32 s4, s62
	v_pk_mul_f32 v[26:27], v[68:69], v[26:27]
	v_pk_mul_f32 v[28:29], v[70:71], v[28:29]
	v_pk_add_f32 v[30:31], v[74:75], 1.0 op_sel_hi:[1,0]
	v_pk_add_f32 v[32:33], v[72:73], 1.0 op_sel_hi:[1,0]
	v_pk_fma_f32 v[28:29], v[30:31], v[28:29], v[78:79]
	v_pk_fma_f32 v[26:27], v[32:33], v[26:27], v[76:77]
	s_nop 0
	v_cvt_pk_bf16_f32 v26, v26, v27
	v_cvt_pk_bf16_f32 v27, v28, v29
	global_store_dwordx2 v[54:55], v[26:27], off offset:512
	s_nop 0
	v_pk_mul_f32 v[22:23], v[80:81], v[22:23]
	v_pk_mul_f32 v[24:25], v[82:83], v[24:25]
	v_pk_add_f32 v[26:27], v[140:141], 1.0 op_sel_hi:[1,0]
	v_pk_add_f32 v[28:29], v[138:139], 1.0 op_sel_hi:[1,0]
	v_pk_fma_f32 v[24:25], v[26:27], v[24:25], v[144:145]
	v_pk_fma_f32 v[22:23], v[28:29], v[22:23], v[142:143]
	s_nop 0
	v_cvt_pk_bf16_f32 v22, v22, v23
	v_cvt_pk_bf16_f32 v23, v24, v25
	global_store_dwordx2 v[54:55], v[22:23], off offset:1024
	s_nop 0
	v_pk_mul_f32 v[18:19], v[18:19], v[146:147]
	v_pk_mul_f32 v[20:21], v[20:21], v[148:149]
	v_pk_add_f32 v[22:23], v[152:153], 1.0 op_sel_hi:[1,0]
	v_pk_add_f32 v[24:25], v[150:151], 1.0 op_sel_hi:[1,0]
	v_pk_fma_f32 v[20:21], v[20:21], v[22:23], v[160:161]
	v_pk_fma_f32 v[18:19], v[18:19], v[24:25], v[158:159]
	s_nop 0
	v_cvt_pk_bf16_f32 v18, v18, v19
	v_cvt_pk_bf16_f32 v19, v20, v21
	global_store_dwordx2 v[54:55], v[18:19], off offset:1536
	s_nop 0
	v_pk_mul_f32 v[14:15], v[14:15], v[162:163]
	v_pk_mul_f32 v[16:17], v[16:17], v[164:165]
	v_pk_add_f32 v[18:19], v[176:177], 1.0 op_sel_hi:[1,0]
	v_pk_add_f32 v[20:21], v[174:175], 1.0 op_sel_hi:[1,0]
	v_pk_fma_f32 v[16:17], v[16:17], v[18:19], v[180:181]
	v_pk_fma_f32 v[14:15], v[14:15], v[20:21], v[178:179]
	s_nop 0
	v_cvt_pk_bf16_f32 v14, v14, v15
	v_cvt_pk_bf16_f32 v15, v16, v17
	global_store_dwordx2 v[54:55], v[14:15], off offset:2048
	s_nop 0
	v_pk_mul_f32 v[10:11], v[10:11], v[182:183]
	v_pk_mul_f32 v[12:13], v[12:13], v[184:185]
	v_pk_add_f32 v[14:15], v[188:189], 1.0 op_sel_hi:[1,0]
	v_pk_add_f32 v[16:17], v[186:187], 1.0 op_sel_hi:[1,0]
	v_pk_fma_f32 v[12:13], v[12:13], v[14:15], v[192:193]
	v_pk_fma_f32 v[10:11], v[10:11], v[16:17], v[190:191]
	s_nop 0
	v_cvt_pk_bf16_f32 v10, v10, v11
	v_cvt_pk_bf16_f32 v11, v12, v13
	global_store_dwordx2 v[54:55], v[10:11], off offset:2560
	s_nop 0
	v_pk_mul_f32 v[6:7], v[6:7], v[202:203]
	v_pk_mul_f32 v[8:9], v[8:9], v[204:205]
	v_pk_add_f32 v[10:11], v[212:213], 1.0 op_sel_hi:[1,0]
	v_pk_add_f32 v[12:13], v[210:211], 1.0 op_sel_hi:[1,0]
	v_pk_fma_f32 v[8:9], v[8:9], v[10:11], v[216:217]
	v_pk_fma_f32 v[6:7], v[6:7], v[12:13], v[214:215]
	s_nop 0
	v_cvt_pk_bf16_f32 v6, v6, v7
	v_cvt_pk_bf16_f32 v7, v8, v9
	global_store_dwordx2 v[54:55], v[6:7], off offset:3072
	s_nop 0
	v_pk_mul_f32 v[2:3], v[2:3], v[218:219]
	v_pk_mul_f32 v[4:5], v[4:5], v[220:221]
	v_pk_add_f32 v[6:7], v[224:225], 1.0 op_sel_hi:[1,0]
	v_pk_add_f32 v[8:9], v[222:223], 1.0 op_sel_hi:[1,0]
	v_pk_fma_f32 v[4:5], v[4:5], v[6:7], v[242:243]
	v_pk_fma_f32 v[2:3], v[2:3], v[8:9], v[240:241]
	s_nop 0
	v_cvt_pk_bf16_f32 v2, v2, v3
	v_cvt_pk_bf16_f32 v3, v4, v5
	global_store_dwordx2 v[54:55], v[2:3], off offset:3584
	s_cbranch_scc1 .LBB0_163

; #define GAS __attribute__((address_space(1)))
; DI void phase_norm(const Ctx& C, const float* xlat, const float* xctx, bf16_t* H, const float* gn, const float* modl, int sh_off, int sc_off, int nrows, const float* part, int nsplit, float* xs_out) {
;     ...
;         for (int j = 0; j < 8; ++j) s += (v[j].x * v[j].x + v[j].y * v[j].y) + (v[j].z * v[j].z + v[j].w * v[j].w);
;         const float rstd = 1.f / sqrtf(wave_sum(s, lane) * (1.f / DM) + EPS);
;         GAS u32x2* o8 = (GAS u32x2*)(H + (size_t)row * DM) + lane;
; #pragma unroll
;         for (int j = 0; j < 8; ++j) { const int col = 4 * lane + 256 * j;
;             const f32x4 g = *(const GAS f32x4*)(gn + col), sc = *(const GAS f32x4*)(mb + sc_off + col), sh = *(const GAS f32x4*)(mb + sh_off + col);
.LBB0_685:
	s_waitcnt vmcnt(0)
	v_mov_b32_e32 v36, v31
	v_mov_b32_e32 v37, v27
	v_mov_b32_e32 v34, v30
	v_mov_b32_e32 v35, v26
	v_pk_mul_f32 v[36:37], v[36:37], v[36:37]
	v_mov_b32_e32 v38, v33
	v_mov_b32_e32 v39, v29
	v_pk_fma_f32 v[34:35], v[34:35], v[34:35], v[36:37]
	v_mov_b32_e32 v36, v32
	v_mov_b32_e32 v37, v28
	v_pk_mul_f32 v[38:39], v[38:39], v[38:39]
	s_min_i32 s0, s4, 0x2000
	v_pk_fma_f32 v[36:37], v[36:37], v[36:37], v[38:39]
	v_pk_mul_f32 v[38:39], v[22:23], v[22:23]
	v_pk_add_f32 v[34:35], v[34:35], v[36:37]
	v_pk_mul_f32 v[36:37], v[24:25], v[24:25]
	v_pk_add_f32 v[34:35], v[34:35], v[34:35] op_sel:[0,1] op_sel_hi:[1,0]
	v_pk_mov_b32 v[40:41], v[38:39], v[36:37] op_sel:[1,0]
	v_mov_b32_e32 v39, v37
	v_pk_add_f32 v[36:37], v[40:41], v[38:39]
	v_mul_f32_e32 v38, v14, v14
	v_mul_f32_e32 v39, v15, v15
	v_pk_add_f32 v[36:37], v[36:37], v[36:37] op_sel:[0,1] op_sel_hi:[1,0]
	v_mov_b32_e32 v35, v38
	v_mov_b32_e32 v37, v39
	v_pk_add_f32 v[34:35], v[34:35], v[36:37]
	v_mul_f32_e32 v36, v19, v19
	v_mul_f32_e32 v38, v21, v21
	v_mul_f32_e32 v40, v16, v16
	v_mul_f32_e32 v41, v17, v17
	v_pk_fma_f32 v[36:37], v[18:19], v[18:19], v[36:37] op_sel_hi:[1,1,0]
	v_pk_fma_f32 v[38:39], v[20:21], v[20:21], v[38:39] op_sel_hi:[1,1,0]
	v_mov_b32_e32 v37, v40
	v_mov_b32_e32 v39, v41
	v_pk_add_f32 v[36:37], v[36:37], v[38:39]
	v_pk_mul_f32 v[38:39], v[10:11], v[10:11]
	v_pk_add_f32 v[34:35], v[34:35], v[36:37]
	v_pk_mul_f32 v[36:37], v[12:13], v[12:13]
	s_ashr_i32 s0, s0, 11
	v_pk_mov_b32 v[40:41], v[38:39], v[36:37] op_sel:[1,0]
	v_mov_b32_e32 v39, v37
	v_pk_add_f32 v[36:37], v[40:41], v[38:39]
	v_mul_f32_e32 v38, v2, v2
	v_mul_f32_e32 v39, v3, v3
	v_pk_add_f32 v[34:35], v[34:35], v[34:35] op_sel:[0,1] op_sel_hi:[1,0]
	v_pk_add_f32 v[36:37], v[36:37], v[36:37] op_sel:[0,1] op_sel_hi:[1,0]
	s_mul_hi_i32 s1, s0, 0xc000
	s_mul_i32 s0, s0, 0xc000
	v_mov_b32_e32 v35, v38
	v_mov_b32_e32 v37, v39
	s_add_u32 s0, s92, s0
	v_pk_add_f32 v[34:35], v[34:35], v[36:37]
	v_mul_f32_e32 v36, v7, v7
	v_mul_f32_e32 v38, v9, v9
	s_addc_u32 s1, s56, s1
	v_mul_f32_e32 v40, v4, v4
	v_mul_f32_e32 v41, v5, v5
	v_pk_fma_f32 v[36:37], v[6:7], v[6:7], v[36:37] op_sel_hi:[1,1,0]
	v_pk_fma_f32 v[38:39], v[8:9], v[8:9], v[38:39] op_sel_hi:[1,1,0]
	v_mov_b32_e32 v37, v40
	v_mov_b32_e32 v39, v41
	v_lshl_add_u64 v[46:47], v[122:123], 2, s[0:1]
	v_pk_add_f32 v[36:37], v[36:37], v[38:39]
	v_add_co_u32_e32 v48, vcc, s20, v46
	v_pk_add_f32 v[34:35], v[34:35], v[36:37]
	s_nop 0
	v_addc_co_u32_e32 v49, vcc, 0, v47, vcc
	v_add_f32_e32 v50, v34, v35
	global_load_dwordx4 v[34:37], v[124:125], off
	global_load_dwordx4 v[38:41], v[48:49], off offset:-4096
	global_load_dwordx4 v[42:45], v[46:47], off
	v_lshl_add_u64 v[134:135], v[46:47], 0, s[44:45]
	v_add_co_u32_e32 v154, vcc, s41, v46
	s_nop 1
	v_addc_co_u32_e32 v155, vcc, 0, v47, vcc
	global_load_dwordx4 v[68:71], v[124:125], off offset:1024
	global_load_dwordx4 v[72:75], v[134:135], off offset:1024
	global_load_dwordx4 v[76:79], v[46:47], off offset:1024
	global_load_dwordx4 v[80:83], v[124:125], off offset:2048
	global_load_dwordx4 v[138:141], v[134:135], off offset:2048
	global_load_dwordx4 v[142:145], v[46:47], off offset:2048
	global_load_dwordx4 v[146:149], v[124:125], off offset:3072
	global_load_dwordx4 v[150:153], v[134:135], off offset:3072
	global_load_dwordx4 v[158:161], v[46:47], off offset:3072
	global_load_dwordx4 v[162:165], v[126:127], off
	global_load_dwordx4 v[174:177], v[48:49], off
	global_load_dwordx4 v[178:181], v[154:155], off
	global_load_dwordx4 v[182:185], v[128:129], off
	global_load_dwordx4 v[186:189], v[48:49], off offset:1024
	global_load_dwordx4 v[190:193], v[154:155], off offset:1024
	global_load_dwordx4 v[202:205], v[130:131], off
	global_load_dwordx4 v[210:213], v[48:49], off offset:2048
	global_load_dwordx4 v[214:217], v[154:155], off offset:2048
	global_load_dwordx4 v[218:221], v[132:133], off
	global_load_dwordx4 v[222:225], v[48:49], off offset:3072
	global_load_dwordx4 v[240:243], v[154:155], off offset:3072
	ds_bpermute_b32 v51, v0, v50
	s_add_u32 s4, s4, s6
	s_addc_u32 s5, s5, s7
	s_waitcnt lgkmcnt(0)
	v_add_f32_e32 v50, v50, v51
	ds_bpermute_b32 v51, v168, v50
	s_waitcnt lgkmcnt(0)
	v_add_f32_e32 v50, v50, v51
	ds_bpermute_b32 v51, v169, v50
	s_waitcnt lgkmcnt(0)
	v_add_f32_e32 v50, v50, v51
	ds_bpermute_b32 v51, v170, v50
	s_waitcnt lgkmcnt(0)
	v_add_f32_e32 v50, v50, v51
	ds_bpermute_b32 v51, v171, v50
	s_waitcnt lgkmcnt(0)
	v_add_f32_e32 v50, v50, v51
	ds_bpermute_b32 v51, v172, v50
	s_waitcnt lgkmcnt(0)
; #define GAS __attribute__((address_space(1)))
; DI unsigned pk2(float lo, float hi) { f32x2 v = {lo, hi}; bf16x2_t b = __builtin_convertvector(v, bf16x2_t); return __builtin_bit_cast(unsigned, b); }
; DI void phase_norm(const Ctx& C, const float* xlat, const float* xctx, bf16_t* H, const float* gn, const float* modl, int sh_off, int sc_off, int nrows, const float* part, int nsplit, float* xs_out) {
;     ...
;         const float rstd = 1.f / sqrtf(wave_sum(s, lane) * (1.f / DM) + EPS);
;         GAS u32x2* o8 = (GAS u32x2*)(H + (size_t)row * DM) + lane;
; #pragma unroll
;         for (int j = 0; j < 8; ++j) { const int col = 4 * lane + 256 * j;
;             const f32x4 g = *(const GAS f32x4*)(gn + col), sc = *(const GAS f32x4*)(mb + sc_off + col), sh = *(const GAS f32x4*)(mb + sh_off + col);
;             const f32x4 y = v[j] * rstd * g * (sc + 1.f) + sh;
;             u32x2 w; w.x = pk2(y.x, y.y); w.y = pk2(y.z, y.w); o8[64 * j] = w; }
	v_add_f32_e32 v50, v50, v51
	v_fmamk_f32 v50, v50, 0x3a000000, v227
	v_mul_f32_e32 v51, 0x4f800000, v50
	v_cmp_gt_f32_e32 vcc, s67, v50
	s_nop 1
	v_cndmask_b32_e32 v50, v50, v51, vcc
	v_sqrt_f32_e32 v51, v50
	s_nop 0
	v_add_u32_e32 v52, -1, v51
	v_fma_f32 v53, -v52, v51, v50
	v_cmp_ge_f32_e64 s[0:1], 0, v53
	v_add_u32_e32 v53, 1, v51
	s_nop 0
	v_cndmask_b32_e64 v52, v51, v52, s[0:1]
	v_fma_f32 v51, -v53, v51, v50
	v_cmp_lt_f32_e64 s[0:1], 0, v51
	s_nop 1
	v_cndmask_b32_e64 v51, v52, v53, s[0:1]
	v_mul_f32_e32 v52, 0x37800000, v51
	v_cndmask_b32_e32 v51, v51, v52, vcc
	v_cmp_class_f32_e32 vcc, v50, v228
	s_nop 1
	v_cndmask_b32_e32 v50, v51, v50, vcc
	v_div_scale_f32 v51, s[0:1], v50, v50, 1.0
	v_rcp_f32_e32 v52, v51
	s_nop 0
	v_fma_f32 v53, -v51, v52, 1.0
	v_fmac_f32_e32 v52, v53, v52
	v_div_scale_f32 v53, vcc, 1.0, v50, 1.0
	v_mul_f32_e32 v54, v53, v52
	v_fma_f32 v55, -v51, v54, v53
	v_fmac_f32_e32 v54, v55, v52
	v_fma_f32 v51, -v51, v54, v53
	v_div_fmas_f32 v51, v51, v52, v54
	v_div_fixup_f32 v50, v51, v50, 1.0
	v_pk_mul_f32 v[32:33], v[32:33], v[50:51] op_sel_hi:[1,0]
	v_pk_mul_f32 v[30:31], v[30:31], v[50:51] op_sel_hi:[1,0]
	s_waitcnt vmcnt(0)
	v_pk_mul_f32 v[32:33], v[36:37], v[32:33]
	v_pk_mul_f32 v[30:31], v[34:35], v[30:31]
	v_pk_add_f32 v[34:35], v[40:41], 1.0 op_sel_hi:[1,0]
	v_pk_add_f32 v[36:37], v[38:39], 1.0 op_sel_hi:[1,0]
	v_pk_fma_f32 v[32:33], v[34:35], v[32:33], v[44:45]
	v_pk_fma_f32 v[30:31], v[36:37], v[30:31], v[42:43]
	v_lshl_add_u64 v[52:53], v[206:207], 3, s[8:9]
	v_cvt_pk_bf16_f32 v30, v30, v31
	v_cvt_pk_bf16_f32 v31, v32, v33
	global_store_dwordx2 v[52:53], v[30:31], off
	v_pk_mul_f32 v[28:29], v[28:29], v[50:51] op_sel_hi:[1,0]
	v_pk_mul_f32 v[26:27], v[26:27], v[50:51] op_sel_hi:[1,0]
	v_pk_mul_f32 v[24:25], v[24:25], v[50:51] op_sel_hi:[1,0]
	v_pk_mul_f32 v[22:23], v[22:23], v[50:51] op_sel_hi:[1,0]
	v_pk_mul_f32 v[20:21], v[20:21], v[50:51] op_sel_hi:[1,0]
	v_pk_mul_f32 v[18:19], v[18:19], v[50:51] op_sel_hi:[1,0]
	v_pk_mul_f32 v[16:17], v[16:17], v[50:51] op_sel_hi:[1,0]
	v_pk_mul_f32 v[14:15], v[14:15], v[50:51] op_sel_hi:[1,0]
	v_pk_mul_f32 v[12:13], v[12:13], v[50:51] op_sel_hi:[1,0]
	v_pk_mul_f32 v[10:11], v[10:11], v[50:51] op_sel_hi:[1,0]
	v_pk_mul_f32 v[8:9], v[8:9], v[50:51] op_sel_hi:[1,0]
	v_pk_mul_f32 v[6:7], v[6:7], v[50:51] op_sel_hi:[1,0]
	v_pk_mul_f32 v[4:5], v[4:5], v[50:51] op_sel_hi:[1,0]
	v_pk_mul_f32 v[2:3], v[2:3], v[50:51] op_sel_hi:[1,0]
	s_add_u32 s8, s8, s10
	s_addc_u32 s9, s9, s11
	s_cmpk_gt_i32 s4, 0x23ff
	v_pk_mul_f32 v[26:27], v[68:69], v[26:27]
	v_pk_mul_f32 v[28:29], v[70:71], v[28:29]
	v_pk_add_f32 v[30:31], v[74:75], 1.0 op_sel_hi:[1,0]
	v_pk_add_f32 v[32:33], v[72:73], 1.0 op_sel_hi:[1,0]
	v_pk_fma_f32 v[28:29], v[30:31], v[28:29], v[78:79]
	v_pk_fma_f32 v[26:27], v[32:33], v[26:27], v[76:77]
	s_nop 0
	v_cvt_pk_bf16_f32 v26, v26, v27
	v_cvt_pk_bf16_f32 v27, v28, v29
	global_store_dwordx2 v[52:53], v[26:27], off offset:512
	s_nop 0
	v_pk_mul_f32 v[22:23], v[80:81], v[22:23]
	v_pk_mul_f32 v[24:25], v[82:83], v[24:25]
	v_pk_add_f32 v[26:27], v[140:141], 1.0 op_sel_hi:[1,0]
	v_pk_add_f32 v[28:29], v[138:139], 1.0 op_sel_hi:[1,0]
	v_pk_fma_f32 v[24:25], v[26:27], v[24:25], v[144:145]
	v_pk_fma_f32 v[22:23], v[28:29], v[22:23], v[142:143]
	s_nop 0
	v_cvt_pk_bf16_f32 v22, v22, v23
	v_cvt_pk_bf16_f32 v23, v24, v25
	global_store_dwordx2 v[52:53], v[22:23], off offset:1024
	s_nop 0
	v_pk_mul_f32 v[18:19], v[18:19], v[146:147]
	v_pk_mul_f32 v[20:21], v[20:21], v[148:149]
	v_pk_add_f32 v[22:23], v[152:153], 1.0 op_sel_hi:[1,0]
	v_pk_add_f32 v[24:25], v[150:151], 1.0 op_sel_hi:[1,0]
	v_pk_fma_f32 v[20:21], v[20:21], v[22:23], v[160:161]
	v_pk_fma_f32 v[18:19], v[18:19], v[24:25], v[158:159]
	v_cvt_pk_bf16_f32 v18, v18, v19
	v_cvt_pk_bf16_f32 v19, v20, v21
	global_store_dwordx2 v[52:53], v[18:19], off offset:1536
	s_nop 0
	v_pk_mul_f32 v[14:15], v[14:15], v[162:163]
	v_pk_mul_f32 v[16:17], v[16:17], v[164:165]
	v_pk_add_f32 v[18:19], v[176:177], 1.0 op_sel_hi:[1,0]
	v_pk_add_f32 v[20:21], v[174:175], 1.0 op_sel_hi:[1,0]
	v_pk_fma_f32 v[16:17], v[16:17], v[18:19], v[180:181]
	v_pk_fma_f32 v[14:15], v[14:15], v[20:21], v[178:179]
	s_nop 0
	v_cvt_pk_bf16_f32 v14, v14, v15
	v_cvt_pk_bf16_f32 v15, v16, v17
	global_store_dwordx2 v[52:53], v[14:15], off offset:2048
	s_nop 0
	v_pk_mul_f32 v[10:11], v[10:11], v[182:183]
	v_pk_mul_f32 v[12:13], v[12:13], v[184:185]
	v_pk_add_f32 v[14:15], v[188:189], 1.0 op_sel_hi:[1,0]
	v_pk_add_f32 v[16:17], v[186:187], 1.0 op_sel_hi:[1,0]
	v_pk_fma_f32 v[12:13], v[12:13], v[14:15], v[192:193]
	v_pk_fma_f32 v[10:11], v[10:11], v[16:17], v[190:191]
	s_nop 0
	v_cvt_pk_bf16_f32 v10, v10, v11
	v_cvt_pk_bf16_f32 v11, v12, v13
	global_store_dwordx2 v[52:53], v[10:11], off offset:2560
	s_nop 0
	v_pk_mul_f32 v[6:7], v[6:7], v[202:203]
	v_pk_mul_f32 v[8:9], v[8:9], v[204:205]
	v_pk_add_f32 v[10:11], v[212:213], 1.0 op_sel_hi:[1,0]
	v_pk_add_f32 v[12:13], v[210:211], 1.0 op_sel_hi:[1,0]
	v_pk_fma_f32 v[8:9], v[8:9], v[10:11], v[216:217]
	v_pk_fma_f32 v[6:7], v[6:7], v[12:13], v[214:215]
	s_nop 0
	v_cvt_pk_bf16_f32 v6, v6, v7
	v_cvt_pk_bf16_f32 v7, v8, v9
	global_store_dwordx2 v[52:53], v[6:7], off offset:3072
	s_nop 0
	v_pk_mul_f32 v[2:3], v[2:3], v[218:219]
	v_pk_mul_f32 v[4:5], v[4:5], v[220:221]
	v_pk_add_f32 v[6:7], v[224:225], 1.0 op_sel_hi:[1,0]
	v_pk_add_f32 v[8:9], v[222:223], 1.0 op_sel_hi:[1,0]
	v_pk_fma_f32 v[4:5], v[4:5], v[6:7], v[242:243]
	v_pk_fma_f32 v[2:3], v[2:3], v[8:9], v[240:241]
	s_nop 0
	v_cvt_pk_bf16_f32 v2, v2, v3
	v_cvt_pk_bf16_f32 v3, v4, v5
	global_store_dwordx2 v[52:53], v[2:3], off offset:3584
	s_cbranch_scc1 .LBB0_688

; #define GAS __attribute__((address_space(1)))
; DI void phase_norm(const Ctx& C, const float* xlat, const float* xctx, bf16_t* H, const float* gn, const float* modl, int sh_off, int sc_off, int nrows, const float* part, int nsplit, float* xs_out) {
;     ...
;     for (int row = gw; row < nrows; row += NGW) {
;         const int b = row < NLAT ? (row >> 11) : 4;
;         const float* mb = modl + (size_t)b * MODW;
;         const GAS f32x4* xr = (const GAS f32x4*)(row < NLAT ? xlat + (size_t)row * DM : xctx + (size_t)(row - NLAT) * DM) + lane;
;         f32x4 v[8]; float s = 0.f;
; #pragma unroll
;         for (int j = 0; j < 8; ++j) v[j] = __builtin_nontemporal_load(xr + 64 * j);
;         if (part != nullptr && row >= NLAT) {
;             for (int kb = 0; kb < nsplit; kb += 4) {
;                 f32x4 t[4][8];
; #pragma unroll
;                 for (int q = 0; q < 4; ++q) { const GAS f32x4* pr = (const GAS f32x4*)(part + ((size_t)(kb + q) * NCTX + (row - NLAT)) * DM) + lane;
; #pragma unroll
;                     for (int j = 0; j < 8; ++j) t[q][j] = __builtin_nontemporal_load(pr + 64 * j); }
; #pragma unroll
;                 for (int j = 0; j < 8; ++j) v[j] += (t[0][j] + t[1][j]) + (t[2][j] + t[3][j]); }
;             GAS f32x4* xo = (GAS f32x4*)(xs_out + (size_t)row * DM) + lane;
; #pragma unroll
;             for (int j = 0; j < 8; ++j) xo[64 * j] = v[j];
;         }
; #pragma unroll
;         for (int j = 0; j < 8; ++j) s += (v[j].x * v[j].x + v[j].y * v[j].y) + (v[j].z * v[j].z + v[j].w * v[j].w);
.LBB0_692:
	s_min_i32 s0, s4, 0x2000
	s_ashr_i32 s0, s0, 11
	s_mul_hi_i32 s1, s0, 0xc000
	s_mul_i32 s0, s0, 0xc000
	s_add_u32 s12, s92, s0
	s_addc_u32 s13, s56, s1
	s_add_i32 s0, s4, 0xffffe000
	s_cmpk_lt_i32 s4, 0x2000
	s_cselect_b32 s1, s5, 0
	s_cselect_b32 s0, s4, s0
	s_cselect_b32 s18, s15, s17
	s_cselect_b32 s19, s14, s16
	s_lshl_b64 s[0:1], s[0:1], 13
	s_add_u32 s0, s19, s0
	s_addc_u32 s1, s18, s1
	v_lshl_add_u64 v[2:3], v[206:207], 4, s[0:1]
	global_load_dwordx4 v[30:33], v[2:3], off nt
	global_load_dwordx4 v[26:29], v[2:3], off offset:1024 nt
	global_load_dwordx4 v[22:25], v[2:3], off offset:2048 nt
	global_load_dwordx4 v[18:21], v[2:3], off offset:3072 nt
	v_add_co_u32_e32 v2, vcc, s41, v2
	v_lshl_add_u64 v[54:55], v[38:39], 2, s[12:13]
	s_nop 0
	v_addc_co_u32_e32 v3, vcc, 0, v3, vcc
	global_load_dwordx4 v[14:17], v[2:3], off nt
	global_load_dwordx4 v[10:13], v[2:3], off offset:1024 nt
	global_load_dwordx4 v[6:9], v[2:3], off offset:2048 nt
	s_nop 0
	global_load_dwordx4 v[2:5], v[2:3], off offset:3072 nt
	v_lshl_add_u64 v[56:57], v[54:55], 0, s[44:45]
	v_add_co_u32_e32 v134, vcc, s20, v54
	s_nop 1
	v_addc_co_u32_e32 v135, vcc, 0, v55, vcc
	v_add_co_u32_e32 v154, vcc, s41, v54
	s_nop 1
	v_addc_co_u32_e32 v155, vcc, 0, v55, vcc
	global_load_dwordx4 v[158:161], v[40:41], off
	global_load_dwordx4 v[162:165], v[134:135], off offset:-4096
	global_load_dwordx4 v[166:169], v[54:55], off
	global_load_dwordx4 v[170:173], v[40:41], off offset:1024
	global_load_dwordx4 v[174:177], v[56:57], off offset:1024
	global_load_dwordx4 v[178:181], v[54:55], off offset:1024
	global_load_dwordx4 v[182:185], v[40:41], off offset:2048
	global_load_dwordx4 v[186:189], v[56:57], off offset:2048
	global_load_dwordx4 v[190:193], v[54:55], off offset:2048
	global_load_dwordx4 v[210:213], v[40:41], off offset:3072
	global_load_dwordx4 v[214:217], v[56:57], off offset:3072
	global_load_dwordx4 v[218:221], v[54:55], off offset:3072
	global_load_dwordx4 v[222:225], v[42:43], off
	global_load_dwordx4 v[240:243], v[134:135], off
	global_load_dwordx4 v[244:247], v[154:155], off
	global_load_dwordx4 v[138:141], v[44:45], off
	global_load_dwordx4 v[142:145], v[134:135], off offset:1024
	global_load_dwordx4 v[146:149], v[154:155], off offset:1024
	global_load_dwordx4 v[150:153], v[46:47], off
	global_load_dwordx4 v[72:75], v[134:135], off offset:2048
	global_load_dwordx4 v[76:79], v[154:155], off offset:2048
	global_load_dwordx4 v[80:83], v[48:49], off
	global_load_dwordx4 v[202:205], v[134:135], off offset:3072
	global_load_dwordx4 v[130:133], v[154:155], off offset:3072
	s_add_u32 s4, s4, s6
	s_addc_u32 s5, s5, s7
	s_waitcnt vmcnt(31)
	v_mov_b32_e32 v36, v31
	s_waitcnt vmcnt(30)
	v_mov_b32_e32 v37, v27
	v_mov_b32_e32 v34, v30
	v_mov_b32_e32 v35, v26
	v_pk_mul_f32 v[36:37], v[36:37], v[36:37]
	v_mov_b32_e32 v50, v33
	v_mov_b32_e32 v51, v29
	v_pk_fma_f32 v[34:35], v[34:35], v[34:35], v[36:37]
	v_mov_b32_e32 v36, v32
	v_mov_b32_e32 v37, v28
	v_pk_mul_f32 v[50:51], v[50:51], v[50:51]
	s_waitcnt vmcnt(27)
	v_mul_f32_e32 v0, v14, v14
	v_pk_fma_f32 v[36:37], v[36:37], v[36:37], v[50:51]
	v_pk_mul_f32 v[50:51], v[22:23], v[22:23]
	v_pk_add_f32 v[34:35], v[34:35], v[36:37]
	v_pk_mul_f32 v[36:37], v[24:25], v[24:25]
	v_pk_add_f32 v[34:35], v[34:35], v[34:35] op_sel:[0,1] op_sel_hi:[1,0]
	v_pk_mov_b32 v[52:53], v[50:51], v[36:37] op_sel:[1,0]
	v_mov_b32_e32 v51, v37
	v_pk_add_f32 v[36:37], v[52:53], v[50:51]
	v_mul_f32_e32 v50, v15, v15
	v_pk_add_f32 v[36:37], v[36:37], v[36:37] op_sel:[0,1] op_sel_hi:[1,0]
	v_mov_b32_e32 v35, v0
	v_mov_b32_e32 v37, v50
	v_mul_f32_e32 v0, v19, v19
	v_mul_f32_e32 v51, v16, v16
	v_pk_add_f32 v[34:35], v[34:35], v[36:37]
	v_pk_fma_f32 v[36:37], v[18:19], v[18:19], v[0:1] op_sel_hi:[1,1,0]
	v_mul_f32_e32 v0, v21, v21
	v_mul_f32_e32 v52, v17, v17
	v_mov_b32_e32 v37, v51
	v_pk_fma_f32 v[50:51], v[20:21], v[20:21], v[0:1] op_sel_hi:[1,1,0]
	s_waitcnt vmcnt(24)
	v_mul_f32_e32 v0, v2, v2
	v_mov_b32_e32 v51, v52
	v_pk_add_f32 v[36:37], v[36:37], v[50:51]
	v_pk_mul_f32 v[50:51], v[10:11], v[10:11]
	v_pk_add_f32 v[34:35], v[34:35], v[36:37]
	v_pk_mul_f32 v[36:37], v[12:13], v[12:13]
	v_pk_add_f32 v[34:35], v[34:35], v[34:35] op_sel:[0,1] op_sel_hi:[1,0]
	v_pk_mov_b32 v[52:53], v[50:51], v[36:37] op_sel:[1,0]
	v_mov_b32_e32 v51, v37
	v_pk_add_f32 v[36:37], v[52:53], v[50:51]
	v_mul_f32_e32 v50, v3, v3
	v_pk_add_f32 v[36:37], v[36:37], v[36:37] op_sel:[0,1] op_sel_hi:[1,0]
	v_mov_b32_e32 v35, v0
	v_mov_b32_e32 v37, v50
	v_mul_f32_e32 v0, v7, v7
	v_mul_f32_e32 v51, v4, v4
	v_pk_add_f32 v[34:35], v[34:35], v[36:37]
	v_pk_fma_f32 v[36:37], v[6:7], v[6:7], v[0:1] op_sel_hi:[1,1,0]
	v_mul_f32_e32 v0, v9, v9
	v_mul_f32_e32 v52, v5, v5
	v_mov_b32_e32 v37, v51
	v_pk_fma_f32 v[50:51], v[8:9], v[8:9], v[0:1] op_sel_hi:[1,1,0]
	s_nop 0
	v_mov_b32_e32 v51, v52
	v_pk_add_f32 v[36:37], v[36:37], v[50:51]
	s_nop 0
	v_pk_add_f32 v[34:35], v[34:35], v[36:37]
	s_nop 0
	v_add_f32_e32 v0, v34, v35
	ds_bpermute_b32 v34, v62, v0
	s_waitcnt lgkmcnt(0)
	v_add_f32_e32 v0, v0, v34
	ds_bpermute_b32 v34, v63, v0
	s_waitcnt lgkmcnt(0)
	v_add_f32_e32 v0, v0, v34
	ds_bpermute_b32 v34, v64, v0
	s_waitcnt lgkmcnt(0)
	v_add_f32_e32 v0, v0, v34
	ds_bpermute_b32 v34, v65, v0
	s_waitcnt lgkmcnt(0)
	v_add_f32_e32 v0, v0, v34
	ds_bpermute_b32 v34, v66, v0
	s_waitcnt lgkmcnt(0)
	v_add_f32_e32 v0, v0, v34
	ds_bpermute_b32 v34, v67, v0
	s_waitcnt lgkmcnt(0)
; #define GAS __attribute__((address_space(1)))
; DI unsigned pk2(float lo, float hi) { f32x2 v = {lo, hi}; bf16x2_t b = __builtin_convertvector(v, bf16x2_t); return __builtin_bit_cast(unsigned, b); }
; DI void phase_norm(const Ctx& C, const float* xlat, const float* xctx, bf16_t* H, const float* gn, const float* modl, int sh_off, int sc_off, int nrows, const float* part, int nsplit, float* xs_out) {
;     ...
;         const float rstd = 1.f / sqrtf(wave_sum(s, lane) * (1.f / DM) + EPS);
;         GAS u32x2* o8 = (GAS u32x2*)(H + (size_t)row * DM) + lane;
; #pragma unroll
;         for (int j = 0; j < 8; ++j) { const int col = 4 * lane + 256 * j;
;             const f32x4 g = *(const GAS f32x4*)(gn + col), sc = *(const GAS f32x4*)(mb + sc_off + col), sh = *(const GAS f32x4*)(mb + sh_off + col);
;             const f32x4 y = v[j] * rstd * g * (sc + 1.f) + sh;
;             u32x2 w; w.x = pk2(y.x, y.y); w.y = pk2(y.z, y.w); o8[64 * j] = w; }
	v_add_f32_e32 v0, v0, v34
	v_fmamk_f32 v0, v0, 0x3a000000, v227
	v_cmp_gt_f32_e32 vcc, s67, v0
	v_mul_f32_e32 v34, 0x4f800000, v0
	s_nop 0
	v_cndmask_b32_e32 v0, v0, v34, vcc
	v_sqrt_f32_e32 v34, v0
	s_nop 0
	v_add_u32_e32 v35, -1, v34
	v_fma_f32 v36, -v35, v34, v0
	v_cmp_ge_f32_e64 s[0:1], 0, v36
	v_add_u32_e32 v36, 1, v34
	s_nop 0
	v_cndmask_b32_e64 v35, v34, v35, s[0:1]
	v_fma_f32 v34, -v36, v34, v0
	v_cmp_lt_f32_e64 s[0:1], 0, v34
	s_nop 1
	v_cndmask_b32_e64 v34, v35, v36, s[0:1]
	v_mul_f32_e32 v35, 0x37800000, v34
	v_cndmask_b32_e32 v34, v34, v35, vcc
	v_cmp_class_f32_e32 vcc, v0, v228
	s_nop 1
	v_cndmask_b32_e32 v0, v34, v0, vcc
	v_div_scale_f32 v34, s[0:1], v0, v0, 1.0
	v_rcp_f32_e32 v35, v34
	s_nop 0
	v_fma_f32 v36, -v34, v35, 1.0
	v_fmac_f32_e32 v35, v36, v35
	v_div_scale_f32 v36, vcc, 1.0, v0, 1.0
	v_mul_f32_e32 v37, v36, v35
	v_fma_f32 v50, -v34, v37, v36
	v_fmac_f32_e32 v37, v50, v35
	v_fma_f32 v34, -v34, v37, v36
	v_div_fmas_f32 v34, v34, v35, v37
	v_div_fixup_f32 v0, v34, v0, 1.0
	s_nop 0
	v_pk_mul_f32 v[32:33], v[32:33], v[0:1] op_sel_hi:[1,0]
	v_pk_mul_f32 v[30:31], v[30:31], v[0:1] op_sel_hi:[1,0]
	s_waitcnt vmcnt(0)
	v_pk_mul_f32 v[32:33], v[160:161], v[32:33]
	v_pk_mul_f32 v[30:31], v[158:159], v[30:31]
	v_lshl_add_u64 v[50:51], v[206:207], 3, s[8:9]
	v_pk_mul_f32 v[28:29], v[28:29], v[0:1] op_sel_hi:[1,0]
	v_pk_mul_f32 v[26:27], v[26:27], v[0:1] op_sel_hi:[1,0]
	v_pk_mul_f32 v[24:25], v[24:25], v[0:1] op_sel_hi:[1,0]
	v_pk_mul_f32 v[22:23], v[22:23], v[0:1] op_sel_hi:[1,0]
	v_pk_mul_f32 v[20:21], v[20:21], v[0:1] op_sel_hi:[1,0]
	v_pk_mul_f32 v[18:19], v[18:19], v[0:1] op_sel_hi:[1,0]
	v_pk_mul_f32 v[16:17], v[16:17], v[0:1] op_sel_hi:[1,0]
	v_pk_mul_f32 v[14:15], v[14:15], v[0:1] op_sel_hi:[1,0]
	v_pk_mul_f32 v[12:13], v[12:13], v[0:1] op_sel_hi:[1,0]
	v_pk_mul_f32 v[10:11], v[10:11], v[0:1] op_sel_hi:[1,0]
	v_pk_mul_f32 v[8:9], v[8:9], v[0:1] op_sel_hi:[1,0]
	v_pk_mul_f32 v[6:7], v[6:7], v[0:1] op_sel_hi:[1,0]
	v_pk_mul_f32 v[4:5], v[4:5], v[0:1] op_sel_hi:[1,0]
	v_pk_mul_f32 v[2:3], v[2:3], v[0:1] op_sel_hi:[1,0]
	s_add_u32 s8, s8, s10
	s_addc_u32 s9, s9, s11
	s_cmpk_gt_i32 s4, 0x23ff
	v_pk_add_f32 v[58:59], v[164:165], 1.0 op_sel_hi:[1,0]
	v_pk_add_f32 v[60:61], v[162:163], 1.0 op_sel_hi:[1,0]
	v_pk_fma_f32 v[32:33], v[58:59], v[32:33], v[168:169]
	v_pk_fma_f32 v[30:31], v[60:61], v[30:31], v[166:167]
	s_nop 0
	v_cvt_pk_bf16_f32 v30, v30, v31
	v_cvt_pk_bf16_f32 v31, v32, v33
	global_store_dwordx2 v[50:51], v[30:31], off
	s_nop 0
	v_pk_mul_f32 v[26:27], v[170:171], v[26:27]
	v_pk_mul_f32 v[28:29], v[172:173], v[28:29]
	v_pk_add_f32 v[30:31], v[176:177], 1.0 op_sel_hi:[1,0]
	v_pk_add_f32 v[32:33], v[174:175], 1.0 op_sel_hi:[1,0]
	v_pk_fma_f32 v[28:29], v[30:31], v[28:29], v[180:181]
	v_pk_fma_f32 v[26:27], v[32:33], v[26:27], v[178:179]
	s_nop 0
	v_cvt_pk_bf16_f32 v26, v26, v27
	v_cvt_pk_bf16_f32 v27, v28, v29
	global_store_dwordx2 v[50:51], v[26:27], off offset:512
	s_nop 0
	v_pk_mul_f32 v[22:23], v[182:183], v[22:23]
	v_pk_mul_f32 v[24:25], v[184:185], v[24:25]
	v_pk_add_f32 v[26:27], v[188:189], 1.0 op_sel_hi:[1,0]
	v_pk_add_f32 v[28:29], v[186:187], 1.0 op_sel_hi:[1,0]
	v_pk_fma_f32 v[24:25], v[26:27], v[24:25], v[192:193]
	v_pk_fma_f32 v[22:23], v[28:29], v[22:23], v[190:191]
	s_nop 0
	v_cvt_pk_bf16_f32 v22, v22, v23
	v_cvt_pk_bf16_f32 v23, v24, v25
	global_store_dwordx2 v[50:51], v[22:23], off offset:1024
	s_nop 0
	v_pk_mul_f32 v[18:19], v[18:19], v[210:211]
	v_pk_mul_f32 v[20:21], v[20:21], v[212:213]
	v_pk_add_f32 v[22:23], v[216:217], 1.0 op_sel_hi:[1,0]
	v_pk_add_f32 v[24:25], v[214:215], 1.0 op_sel_hi:[1,0]
	v_pk_fma_f32 v[20:21], v[20:21], v[22:23], v[220:221]
	v_pk_fma_f32 v[18:19], v[18:19], v[24:25], v[218:219]
	v_cvt_pk_bf16_f32 v18, v18, v19
	v_cvt_pk_bf16_f32 v19, v20, v21
	global_store_dwordx2 v[50:51], v[18:19], off offset:1536
	s_nop 0
	v_pk_mul_f32 v[14:15], v[14:15], v[222:223]
	v_pk_mul_f32 v[16:17], v[16:17], v[224:225]
	v_pk_add_f32 v[18:19], v[242:243], 1.0 op_sel_hi:[1,0]
	v_pk_add_f32 v[20:21], v[240:241], 1.0 op_sel_hi:[1,0]
	v_pk_fma_f32 v[16:17], v[16:17], v[18:19], v[246:247]
	v_pk_fma_f32 v[14:15], v[14:15], v[20:21], v[244:245]
	s_nop 0
	v_cvt_pk_bf16_f32 v14, v14, v15
	v_cvt_pk_bf16_f32 v15, v16, v17
	global_store_dwordx2 v[50:51], v[14:15], off offset:2048
	s_nop 0
	v_pk_mul_f32 v[10:11], v[10:11], v[138:139]
	v_pk_mul_f32 v[12:13], v[12:13], v[140:141]
	v_pk_add_f32 v[14:15], v[144:145], 1.0 op_sel_hi:[1,0]
	v_pk_add_f32 v[16:17], v[142:143], 1.0 op_sel_hi:[1,0]
	v_pk_fma_f32 v[12:13], v[12:13], v[14:15], v[148:149]
	v_pk_fma_f32 v[10:11], v[10:11], v[16:17], v[146:147]
	s_nop 0
	v_cvt_pk_bf16_f32 v10, v10, v11
	v_cvt_pk_bf16_f32 v11, v12, v13
	global_store_dwordx2 v[50:51], v[10:11], off offset:2560
	s_nop 0
	v_pk_mul_f32 v[6:7], v[6:7], v[150:151]
	v_pk_mul_f32 v[8:9], v[8:9], v[152:153]
	v_pk_add_f32 v[10:11], v[74:75], 1.0 op_sel_hi:[1,0]
	v_pk_add_f32 v[12:13], v[72:73], 1.0 op_sel_hi:[1,0]
	v_pk_fma_f32 v[8:9], v[8:9], v[10:11], v[78:79]
	v_pk_fma_f32 v[6:7], v[6:7], v[12:13], v[76:77]
	s_nop 0
	v_cvt_pk_bf16_f32 v6, v6, v7
	v_cvt_pk_bf16_f32 v7, v8, v9
	global_store_dwordx2 v[50:51], v[6:7], off offset:3072
	s_nop 0
	v_pk_mul_f32 v[2:3], v[2:3], v[80:81]
	v_pk_mul_f32 v[4:5], v[4:5], v[82:83]
	v_pk_add_f32 v[6:7], v[204:205], 1.0 op_sel_hi:[1,0]
	v_pk_add_f32 v[8:9], v[202:203], 1.0 op_sel_hi:[1,0]
	v_pk_fma_f32 v[4:5], v[4:5], v[6:7], v[132:133]
	v_pk_fma_f32 v[2:3], v[2:3], v[8:9], v[130:131]
	s_nop 0
	v_cvt_pk_bf16_f32 v2, v2, v3
	v_cvt_pk_bf16_f32 v3, v4, v5
	global_store_dwordx2 v[50:51], v[2:3], off offset:3584
	s_cbranch_scc0 .LBB0_692
